# softmax epilogue in the sample sub-phase: row max/exp/sum only for the 16-row groups that hold the unit's 32 real rows; waves with no real row skip the normalise+store part (those P rows are never rea
# speedup vs baseline: 1.0017x; 1.0017x over previous
.LBB0_551:
	s_mov_b32 s100, 0xff
	s_cmp_lg_u32 s30, 0
	s_cbranch_scc1 .Lsm1_mask_done
	s_lshr_b32 s101, s51, 2
	s_lshr_b32 s100, s101, 1
	s_and_b32 s100, s100, 1
	s_cmp_eq_u32 s100, s43
	s_mov_b32 s100, 0
	s_cbranch_scc0 .Lsm1_mask_done
	s_lshr_b32 s100, s101, 2
	s_lshl_b32 s100, s100, 2
	s_and_b32 s101, s101, 1
	s_lshl_b32 s101, s101, 1
	s_add_u32 s100, s100, s101
	s_lshl_b32 s100, 3, s100
.Lsm1_mask_done:
	s_mov_b32 s62, 0xff61b1e6
	v_mov_b32_e32 v152, v149
	v_mov_b32_e32 v153, v148
	v_lshlrev_b32_e32 v136, 2, v153
	v_lshl_add_u32 v136, v152, 6, v136
	v_xor_b32_e32 v154, 64, v136
	v_xor_b32_e32 v155, 0x80, v136
	s_mov_b32 s24, s73
	s_mov_b32 s28, s43
	s_lshl_b32 s8, s24, 3
	s_add_i32 s29, s8, 0
	v_cmp_eq_u32_e32 vcc, 0, v152
	s_add_i32 s29, s29, 0x20000
	s_bitcmp1_b32 s100, 0
	s_cbranch_scc0 .Lsm1_g1
	v_max_f32_e32 v137, v131, v131
	v_max_f32_e32 v138, v130, v130
	v_max_f32_e32 v137, v138, v137
	v_max_f32_e32 v138, v127, v127
	v_max_f32_e32 v139, v126, v126
	v_max_f32_e32 v138, v139, v138
	v_max3_f32 v137, v128, v129, v137
	v_max3_f32 v138, v124, v125, v138
	v_max3_f32 v137, v137, s62, v138
	v_max_f32_e32 v138, v123, v123
	v_max_f32_e32 v139, v122, v122
	v_max_f32_e32 v138, v139, v138
	v_max_f32_e32 v139, v119, v119
	v_max_f32_e32 v140, v118, v118
	v_max_f32_e32 v139, v140, v139
	v_max3_f32 v138, v120, v121, v138
	v_max3_f32 v139, v116, v117, v139
	v_max3_f32 v137, v137, v138, v139
	ds_bpermute_b32 v138, v154, v137
	s_waitcnt lgkmcnt(0)
	v_max_f32_e32 v136, v138, v138
	v_max_f32_e32 v136, v137, v136
	ds_bpermute_b32 v137, v155, v136
	s_waitcnt lgkmcnt(0)
	v_max_f32_e32 v137, v137, v137
	v_max_f32_e32 v146, v136, v137
	v_sub_f32_e32 v128, v128, v146
	v_mul_f32_e32 v128, 0x3fb8aa3b, v128
	v_sub_f32_e32 v129, v129, v146
	v_exp_f32_e32 v128, v128
	v_mul_f32_e32 v129, 0x3fb8aa3b, v129
	v_sub_f32_e32 v130, v130, v146
	v_exp_f32_e32 v129, v129
	v_mul_f32_e32 v130, 0x3fb8aa3b, v130
	v_sub_f32_e32 v131, v131, v146
	v_exp_f32_e32 v130, v130
	v_mul_f32_e32 v131, 0x3fb8aa3b, v131
	v_exp_f32_e32 v131, v131
	v_add_f32_e32 v136, 0, v128
	v_add_f32_e32 v136, v129, v136
	v_sub_f32_e32 v124, v124, v146
	v_add_f32_e32 v136, v130, v136
	v_mul_f32_e32 v124, 0x3fb8aa3b, v124
	v_add_f32_e32 v138, v131, v136
	v_exp_f32_e32 v136, v124
	v_sub_f32_e32 v124, v125, v146
	v_mul_f32_e32 v124, 0x3fb8aa3b, v124
	v_exp_f32_e32 v137, v124
	v_sub_f32_e32 v124, v126, v146
	v_sub_f32_e32 v120, v120, v146
	v_mul_f32_e32 v124, 0x3fb8aa3b, v124
	v_mul_f32_e32 v120, 0x3fb8aa3b, v120
	v_exp_f32_e32 v142, v124
	v_sub_f32_e32 v124, v127, v146
	v_exp_f32_e32 v126, v120
	v_sub_f32_e32 v120, v121, v146
	v_mul_f32_e32 v124, 0x3fb8aa3b, v124
	v_mul_f32_e32 v120, 0x3fb8aa3b, v120
	v_exp_f32_e32 v143, v124
	v_exp_f32_e32 v127, v120
	v_sub_f32_e32 v120, v122, v146
	v_sub_f32_e32 v116, v116, v146
	v_add_f32_e32 v124, v136, v138
	v_mul_f32_e32 v120, 0x3fb8aa3b, v120
	v_mul_f32_e32 v116, 0x3fb8aa3b, v116
	v_add_f32_e32 v124, v137, v124
	v_exp_f32_e32 v138, v120
	v_sub_f32_e32 v120, v123, v146
	v_exp_f32_e32 v140, v116
	v_sub_f32_e32 v116, v117, v146
	v_add_f32_e32 v124, v142, v124
	v_mul_f32_e32 v120, 0x3fb8aa3b, v120
	v_mul_f32_e32 v116, 0x3fb8aa3b, v116
	v_add_f32_e32 v124, v143, v124
	v_exp_f32_e32 v139, v120
	v_exp_f32_e32 v141, v116
	v_sub_f32_e32 v116, v118, v146
	v_add_f32_e32 v120, v126, v124
	v_mul_f32_e32 v116, 0x3fb8aa3b, v116
	v_add_f32_e32 v120, v127, v120
	v_exp_f32_e32 v144, v116
	v_sub_f32_e32 v116, v119, v146
	v_add_f32_e32 v120, v138, v120
	v_mul_f32_e32 v116, 0x3fb8aa3b, v116
	v_add_f32_e32 v120, v139, v120
	v_exp_f32_e32 v145, v116
	v_add_f32_e32 v116, v140, v120
	v_add_f32_e32 v116, v141, v116
	v_add_f32_e32 v116, v144, v116
	v_add_f32_e32 v116, v145, v116
	ds_bpermute_b32 v117, v154, v116
	s_waitcnt lgkmcnt(0)
	v_add_f32_e32 v116, v116, v117
	ds_bpermute_b32 v117, v155, v116
	s_and_saveexec_b64 s[8:9], vcc
	s_cbranch_execz .LBB0_553
	s_lshl_b32 s44, s28, 11
	s_add_i32 s44, s29, s44
	s_waitcnt lgkmcnt(0)
	v_add_f32_e32 v147, v116, v117
	v_lshl_add_u32 v116, v153, 5, s44
	ds_write_b64 v116, v[146:147]

.Lsm1_g1:
	s_bitcmp1_b32 s100, 1
	s_cbranch_scc0 .Lsm1_g2
	v_max_f32_e32 v116, v115, v115
	s_waitcnt lgkmcnt(0)
	v_max_f32_e32 v117, v114, v114
	v_max_f32_e32 v116, v117, v116
	v_max_f32_e32 v117, v111, v111
	v_max_f32_e32 v118, v110, v110
	v_max_f32_e32 v117, v118, v117
	v_max3_f32 v116, v112, v113, v116
	v_max3_f32 v117, v108, v109, v117
	v_max3_f32 v116, v116, s62, v117
	v_max_f32_e32 v117, v107, v107
	v_max_f32_e32 v118, v106, v106
	v_max_f32_e32 v117, v118, v117
	v_max_f32_e32 v118, v103, v103
	v_max_f32_e32 v119, v102, v102
	v_max_f32_e32 v118, v119, v118
	v_max3_f32 v117, v104, v105, v117
	v_max3_f32 v118, v100, v101, v118
	v_max3_f32 v116, v116, v117, v118
	ds_bpermute_b32 v117, v154, v116
	s_waitcnt lgkmcnt(0)
	v_max_f32_e32 v117, v117, v117
	v_max_f32_e32 v116, v116, v117
	ds_bpermute_b32 v117, v155, v116
	s_waitcnt lgkmcnt(0)
	v_max_f32_e32 v117, v117, v117
	v_max_f32_e32 v146, v116, v117
	v_sub_f32_e32 v112, v112, v146
	v_mul_f32_e32 v112, 0x3fb8aa3b, v112
	v_sub_f32_e32 v113, v113, v146
	v_exp_f32_e32 v112, v112
	v_mul_f32_e32 v113, 0x3fb8aa3b, v113
	v_sub_f32_e32 v114, v114, v146
	v_exp_f32_e32 v113, v113
	v_mul_f32_e32 v114, 0x3fb8aa3b, v114
	v_sub_f32_e32 v115, v115, v146
	v_exp_f32_e32 v114, v114
	v_mul_f32_e32 v115, 0x3fb8aa3b, v115
	v_exp_f32_e32 v115, v115
	v_add_f32_e32 v116, 0, v112
	v_add_f32_e32 v116, v113, v116
	v_sub_f32_e32 v108, v108, v146
	v_add_f32_e32 v116, v114, v116
	v_mul_f32_e32 v108, 0x3fb8aa3b, v108
	v_add_f32_e32 v118, v115, v116
	v_exp_f32_e32 v116, v108
	v_sub_f32_e32 v108, v109, v146
	v_mul_f32_e32 v108, 0x3fb8aa3b, v108
	v_exp_f32_e32 v117, v108
	v_sub_f32_e32 v108, v110, v146
	v_sub_f32_e32 v104, v104, v146
	v_mul_f32_e32 v108, 0x3fb8aa3b, v108
	v_mul_f32_e32 v104, 0x3fb8aa3b, v104
	v_exp_f32_e32 v122, v108
	v_sub_f32_e32 v108, v111, v146
	v_exp_f32_e32 v110, v104
	v_sub_f32_e32 v104, v105, v146
	v_mul_f32_e32 v108, 0x3fb8aa3b, v108
	v_mul_f32_e32 v104, 0x3fb8aa3b, v104
	v_exp_f32_e32 v123, v108
	v_exp_f32_e32 v111, v104
	v_sub_f32_e32 v104, v106, v146
	v_sub_f32_e32 v100, v100, v146
	v_add_f32_e32 v108, v116, v118
	v_mul_f32_e32 v104, 0x3fb8aa3b, v104
	v_mul_f32_e32 v100, 0x3fb8aa3b, v100
	v_add_f32_e32 v108, v117, v108
	v_exp_f32_e32 v118, v104
	v_sub_f32_e32 v104, v107, v146
	v_exp_f32_e32 v120, v100
	v_sub_f32_e32 v100, v101, v146
	v_add_f32_e32 v108, v122, v108
	v_mul_f32_e32 v104, 0x3fb8aa3b, v104
	v_mul_f32_e32 v100, 0x3fb8aa3b, v100
	v_add_f32_e32 v108, v123, v108
	v_exp_f32_e32 v119, v104
	v_exp_f32_e32 v121, v100
	v_sub_f32_e32 v100, v102, v146
	v_add_f32_e32 v104, v110, v108
	v_mul_f32_e32 v100, 0x3fb8aa3b, v100
	v_add_f32_e32 v104, v111, v104
	v_exp_f32_e32 v124, v100
	v_sub_f32_e32 v100, v103, v146
	v_add_f32_e32 v104, v118, v104
	v_mul_f32_e32 v100, 0x3fb8aa3b, v100
	v_add_f32_e32 v104, v119, v104
	v_exp_f32_e32 v125, v100
	v_add_f32_e32 v100, v120, v104
	v_add_f32_e32 v100, v121, v100
	v_add_f32_e32 v100, v124, v100
	v_add_f32_e32 v100, v125, v100
	ds_bpermute_b32 v101, v154, v100
	s_waitcnt lgkmcnt(0)
	v_add_f32_e32 v100, v100, v101
	ds_bpermute_b32 v101, v155, v100
	s_and_saveexec_b64 s[8:9], vcc
	s_cbranch_execz .LBB0_555
	s_lshl_b32 s44, s28, 11
	s_add_i32 s44, s29, s44
	s_waitcnt lgkmcnt(0)
	v_add_f32_e32 v147, v100, v101
	v_lshl_add_u32 v100, v153, 5, s44
	ds_write_b64 v100, v[146:147] offset:512

.Lsm1_g2:
	s_bitcmp1_b32 s100, 2
	s_cbranch_scc0 .Lsm1_g3
	v_max_f32_e32 v100, v99, v99
	s_waitcnt lgkmcnt(0)
	v_max_f32_e32 v101, v98, v98
	v_max_f32_e32 v100, v101, v100
	v_max_f32_e32 v101, v95, v95
	v_max_f32_e32 v102, v94, v94
	v_max_f32_e32 v101, v102, v101
	v_max3_f32 v100, v96, v97, v100
	v_max3_f32 v101, v92, v93, v101
	v_max3_f32 v100, v100, s62, v101
	v_max_f32_e32 v101, v91, v91
	v_max_f32_e32 v102, v90, v90
	v_max_f32_e32 v101, v102, v101
	v_max_f32_e32 v102, v87, v87
	v_max_f32_e32 v103, v86, v86
	v_max_f32_e32 v102, v103, v102
	v_max3_f32 v101, v88, v89, v101
	v_max3_f32 v102, v84, v85, v102
	v_max3_f32 v100, v100, v101, v102
	ds_bpermute_b32 v101, v154, v100
	s_waitcnt lgkmcnt(0)
	v_max_f32_e32 v101, v101, v101
	v_max_f32_e32 v100, v100, v101
	ds_bpermute_b32 v101, v155, v100
	s_waitcnt lgkmcnt(0)
	v_max_f32_e32 v101, v101, v101
	v_max_f32_e32 v146, v100, v101
	v_sub_f32_e32 v96, v96, v146
	v_mul_f32_e32 v96, 0x3fb8aa3b, v96
	v_sub_f32_e32 v97, v97, v146
	v_exp_f32_e32 v96, v96
	v_mul_f32_e32 v97, 0x3fb8aa3b, v97
	v_sub_f32_e32 v98, v98, v146
	v_exp_f32_e32 v97, v97
	v_mul_f32_e32 v98, 0x3fb8aa3b, v98
	v_sub_f32_e32 v99, v99, v146
	v_exp_f32_e32 v98, v98
	v_mul_f32_e32 v99, 0x3fb8aa3b, v99
	v_exp_f32_e32 v99, v99
	v_add_f32_e32 v100, 0, v96
	v_add_f32_e32 v100, v97, v100
	v_sub_f32_e32 v92, v92, v146
	v_add_f32_e32 v100, v98, v100
	v_mul_f32_e32 v92, 0x3fb8aa3b, v92
	v_add_f32_e32 v102, v99, v100
	v_exp_f32_e32 v100, v92
	v_sub_f32_e32 v92, v93, v146
	v_mul_f32_e32 v92, 0x3fb8aa3b, v92
	v_exp_f32_e32 v101, v92
	v_sub_f32_e32 v92, v94, v146
	v_sub_f32_e32 v88, v88, v146
	v_mul_f32_e32 v92, 0x3fb8aa3b, v92
	v_mul_f32_e32 v88, 0x3fb8aa3b, v88
	v_exp_f32_e32 v106, v92
	v_sub_f32_e32 v92, v95, v146
	v_exp_f32_e32 v94, v88
	v_sub_f32_e32 v88, v89, v146
	v_mul_f32_e32 v92, 0x3fb8aa3b, v92
	v_mul_f32_e32 v88, 0x3fb8aa3b, v88
	v_exp_f32_e32 v107, v92
	v_exp_f32_e32 v95, v88
	v_sub_f32_e32 v88, v90, v146
	v_sub_f32_e32 v84, v84, v146
	v_add_f32_e32 v92, v100, v102
	v_mul_f32_e32 v88, 0x3fb8aa3b, v88
	v_mul_f32_e32 v84, 0x3fb8aa3b, v84
	v_add_f32_e32 v92, v101, v92
	v_exp_f32_e32 v102, v88
	v_sub_f32_e32 v88, v91, v146
	v_exp_f32_e32 v104, v84
	v_sub_f32_e32 v84, v85, v146
	v_add_f32_e32 v92, v106, v92
	v_mul_f32_e32 v88, 0x3fb8aa3b, v88
	v_mul_f32_e32 v84, 0x3fb8aa3b, v84
	v_add_f32_e32 v92, v107, v92
	v_exp_f32_e32 v103, v88
	v_exp_f32_e32 v105, v84
	v_sub_f32_e32 v84, v86, v146
	v_add_f32_e32 v88, v94, v92
	v_mul_f32_e32 v84, 0x3fb8aa3b, v84
	v_add_f32_e32 v88, v95, v88
	v_exp_f32_e32 v108, v84
	v_sub_f32_e32 v84, v87, v146
	v_add_f32_e32 v88, v102, v88
	v_mul_f32_e32 v84, 0x3fb8aa3b, v84
	v_add_f32_e32 v88, v103, v88
	v_exp_f32_e32 v109, v84
	v_add_f32_e32 v84, v104, v88
	v_add_f32_e32 v84, v105, v84
	v_add_f32_e32 v84, v108, v84
	v_add_f32_e32 v84, v109, v84
	ds_bpermute_b32 v85, v154, v84
	s_waitcnt lgkmcnt(0)
	v_add_f32_e32 v84, v84, v85
	ds_bpermute_b32 v85, v155, v84
	s_and_saveexec_b64 s[8:9], vcc
	s_cbranch_execz .LBB0_557
	s_lshl_b32 s44, s28, 11
	s_add_i32 s44, s29, s44
	s_waitcnt lgkmcnt(0)
	v_add_f32_e32 v147, v84, v85
	v_lshl_add_u32 v84, v153, 5, s44
	ds_write_b64 v84, v[146:147] offset:1024

.Lsm1_g3:
	s_bitcmp1_b32 s100, 3
	s_cbranch_scc0 .Lsm1_g4
	v_max_f32_e32 v84, v83, v83
	s_waitcnt lgkmcnt(0)
	v_max_f32_e32 v85, v82, v82
	v_max_f32_e32 v84, v85, v84
	v_max_f32_e32 v85, v79, v79
	v_max_f32_e32 v86, v78, v78
	v_max_f32_e32 v85, v86, v85
	v_max3_f32 v84, v80, v81, v84
	v_max3_f32 v85, v76, v77, v85
	v_max3_f32 v84, v84, s62, v85
	v_max_f32_e32 v85, v75, v75
	v_max_f32_e32 v86, v74, v74
	v_max_f32_e32 v85, v86, v85
	v_max_f32_e32 v86, v71, v71
	v_max_f32_e32 v87, v70, v70
	v_max_f32_e32 v86, v87, v86
	v_max3_f32 v85, v72, v73, v85
	v_max3_f32 v86, v68, v69, v86
	v_max3_f32 v84, v84, v85, v86
	ds_bpermute_b32 v85, v154, v84
	s_waitcnt lgkmcnt(0)
	v_max_f32_e32 v85, v85, v85
	v_max_f32_e32 v84, v84, v85
	ds_bpermute_b32 v85, v155, v84
	s_waitcnt lgkmcnt(0)
	v_max_f32_e32 v85, v85, v85
	v_max_f32_e32 v88, v84, v85
	v_sub_f32_e32 v80, v80, v88
	v_mul_f32_e32 v80, 0x3fb8aa3b, v80
	v_sub_f32_e32 v81, v81, v88
	v_exp_f32_e32 v80, v80
	v_mul_f32_e32 v81, 0x3fb8aa3b, v81
	v_sub_f32_e32 v82, v82, v88
	v_exp_f32_e32 v81, v81
	v_mul_f32_e32 v82, 0x3fb8aa3b, v82
	v_sub_f32_e32 v83, v83, v88
	v_exp_f32_e32 v82, v82
	v_mul_f32_e32 v83, 0x3fb8aa3b, v83
	v_exp_f32_e32 v83, v83
	v_add_f32_e32 v84, 0, v80
	v_add_f32_e32 v84, v81, v84
	v_sub_f32_e32 v76, v76, v88
	v_add_f32_e32 v84, v82, v84
	v_mul_f32_e32 v76, 0x3fb8aa3b, v76
	v_add_f32_e32 v86, v83, v84
	v_exp_f32_e32 v84, v76
	v_sub_f32_e32 v76, v77, v88
	v_mul_f32_e32 v76, 0x3fb8aa3b, v76
	v_exp_f32_e32 v85, v76
	v_sub_f32_e32 v76, v78, v88
	v_mul_f32_e32 v76, 0x3fb8aa3b, v76
	v_exp_f32_e32 v90, v76
	v_sub_f32_e32 v76, v79, v88
	v_mul_f32_e32 v76, 0x3fb8aa3b, v76
	v_exp_f32_e32 v91, v76
	v_add_f32_e32 v76, v84, v86
	v_add_f32_e32 v76, v85, v76
	v_sub_f32_e32 v72, v72, v88
	v_add_f32_e32 v76, v90, v76
	v_mul_f32_e32 v72, 0x3fb8aa3b, v72
	v_add_f32_e32 v86, v91, v76
	v_exp_f32_e32 v76, v72
	v_sub_f32_e32 v72, v73, v88
	v_mul_f32_e32 v72, 0x3fb8aa3b, v72
	v_exp_f32_e32 v77, v72
	v_sub_f32_e32 v72, v74, v88
	v_mul_f32_e32 v72, 0x3fb8aa3b, v72
	v_exp_f32_e32 v78, v72
	v_sub_f32_e32 v72, v75, v88
	v_sub_f32_e32 v68, v68, v88
	v_mul_f32_e32 v72, 0x3fb8aa3b, v72
	v_mul_f32_e32 v68, 0x3fb8aa3b, v68
	v_exp_f32_e32 v79, v72
	v_add_f32_e32 v72, v76, v86
	v_exp_f32_e32 v86, v68
	v_sub_f32_e32 v68, v69, v88
	v_mul_f32_e32 v68, 0x3fb8aa3b, v68
	v_exp_f32_e32 v87, v68
	v_sub_f32_e32 v68, v70, v88
	v_mul_f32_e32 v68, 0x3fb8aa3b, v68
	v_add_f32_e32 v72, v77, v72
	v_exp_f32_e32 v92, v68
	v_sub_f32_e32 v68, v71, v88
	v_add_f32_e32 v72, v78, v72
	v_mul_f32_e32 v68, 0x3fb8aa3b, v68
	v_add_f32_e32 v72, v79, v72
	v_exp_f32_e32 v93, v68
	v_add_f32_e32 v68, v86, v72
	v_add_f32_e32 v68, v87, v68
	v_add_f32_e32 v68, v92, v68
	v_add_f32_e32 v68, v93, v68
	ds_bpermute_b32 v69, v154, v68
	s_waitcnt lgkmcnt(0)
	v_add_f32_e32 v68, v68, v69
	ds_bpermute_b32 v69, v155, v68
	s_and_saveexec_b64 s[8:9], vcc
	s_cbranch_execz .LBB0_559
	s_lshl_b32 s44, s28, 11
	s_add_i32 s44, s29, s44
	s_waitcnt lgkmcnt(0)
	v_add_f32_e32 v89, v68, v69
	v_lshl_add_u32 v68, v153, 5, s44
	ds_write_b64 v68, v[88:89] offset:1536

.Lsm1_g4:
	s_bitcmp1_b32 s100, 4
	s_cbranch_scc0 .Lsm1_g5
	v_max_f32_e32 v68, v67, v67
	s_waitcnt lgkmcnt(0)
	v_max_f32_e32 v69, v66, v66
	v_max_f32_e32 v68, v69, v68
	v_max_f32_e32 v69, v63, v63
	v_max_f32_e32 v70, v62, v62
	v_max_f32_e32 v69, v70, v69
	v_max3_f32 v68, v64, v65, v68
	v_max3_f32 v69, v60, v61, v69
	v_max3_f32 v68, v68, s62, v69
	v_max_f32_e32 v69, v59, v59
	v_max_f32_e32 v70, v58, v58
	v_max_f32_e32 v69, v70, v69
	v_max_f32_e32 v70, v55, v55
	v_max_f32_e32 v71, v54, v54
	v_max_f32_e32 v70, v71, v70
	v_max3_f32 v69, v56, v57, v69
	v_max3_f32 v70, v52, v53, v70
	v_max3_f32 v68, v68, v69, v70
	ds_bpermute_b32 v69, v154, v68
	s_waitcnt lgkmcnt(0)
	v_max_f32_e32 v69, v69, v69
	v_max_f32_e32 v68, v68, v69
	ds_bpermute_b32 v69, v155, v68
	s_waitcnt lgkmcnt(0)
	v_max_f32_e32 v69, v69, v69
	v_max_f32_e32 v88, v68, v69
	v_sub_f32_e32 v64, v64, v88
	v_mul_f32_e32 v64, 0x3fb8aa3b, v64
	v_sub_f32_e32 v65, v65, v88
	v_exp_f32_e32 v64, v64
	v_mul_f32_e32 v65, 0x3fb8aa3b, v65
	v_sub_f32_e32 v66, v66, v88
	v_exp_f32_e32 v65, v65
	v_mul_f32_e32 v66, 0x3fb8aa3b, v66
	v_sub_f32_e32 v67, v67, v88
	v_exp_f32_e32 v66, v66
	v_mul_f32_e32 v67, 0x3fb8aa3b, v67
	v_exp_f32_e32 v67, v67
	v_add_f32_e32 v68, 0, v64
	v_add_f32_e32 v68, v65, v68
	v_sub_f32_e32 v60, v60, v88
	v_add_f32_e32 v68, v66, v68
	v_mul_f32_e32 v60, 0x3fb8aa3b, v60
	v_add_f32_e32 v70, v67, v68
	v_exp_f32_e32 v68, v60
	v_sub_f32_e32 v60, v61, v88
	v_mul_f32_e32 v60, 0x3fb8aa3b, v60
	v_exp_f32_e32 v69, v60
	v_sub_f32_e32 v60, v62, v88
	v_mul_f32_e32 v60, 0x3fb8aa3b, v60
	v_exp_f32_e32 v72, v60
	v_sub_f32_e32 v60, v63, v88
	v_mul_f32_e32 v60, 0x3fb8aa3b, v60
	v_exp_f32_e32 v73, v60
	v_add_f32_e32 v60, v68, v70
	v_add_f32_e32 v60, v69, v60
	v_sub_f32_e32 v56, v56, v88
	v_add_f32_e32 v60, v72, v60
	v_mul_f32_e32 v56, 0x3fb8aa3b, v56
	v_add_f32_e32 v70, v73, v60
	v_exp_f32_e32 v60, v56
	v_sub_f32_e32 v56, v57, v88
	v_mul_f32_e32 v56, 0x3fb8aa3b, v56
	v_exp_f32_e32 v61, v56
	v_sub_f32_e32 v56, v58, v88
	v_mul_f32_e32 v56, 0x3fb8aa3b, v56
	v_exp_f32_e32 v62, v56
	v_sub_f32_e32 v56, v59, v88
	v_sub_f32_e32 v52, v52, v88
	v_mul_f32_e32 v56, 0x3fb8aa3b, v56
	v_mul_f32_e32 v52, 0x3fb8aa3b, v52
	v_exp_f32_e32 v63, v56
	v_add_f32_e32 v56, v60, v70
	v_exp_f32_e32 v70, v52
	v_sub_f32_e32 v52, v53, v88
	v_mul_f32_e32 v52, 0x3fb8aa3b, v52
	v_exp_f32_e32 v71, v52
	v_sub_f32_e32 v52, v54, v88
	v_mul_f32_e32 v52, 0x3fb8aa3b, v52
	v_add_f32_e32 v56, v61, v56
	v_exp_f32_e32 v74, v52
	v_sub_f32_e32 v52, v55, v88
	v_add_f32_e32 v56, v62, v56
	v_mul_f32_e32 v52, 0x3fb8aa3b, v52
	v_add_f32_e32 v56, v63, v56
	v_exp_f32_e32 v75, v52
	v_add_f32_e32 v52, v70, v56
	v_add_f32_e32 v52, v71, v52
	v_add_f32_e32 v52, v74, v52
	v_add_f32_e32 v52, v75, v52
	ds_bpermute_b32 v53, v154, v52
	s_waitcnt lgkmcnt(0)
	v_add_f32_e32 v52, v52, v53
	ds_bpermute_b32 v53, v155, v52
	s_and_saveexec_b64 s[8:9], vcc
	s_cbranch_execz .LBB0_561
	s_lshl_b32 s44, s28, 11
	s_add_i32 s44, s29, s44
	s_waitcnt lgkmcnt(0)
	v_add_f32_e32 v89, v52, v53
	v_lshl_add_u32 v52, v153, 5, s44
	ds_write_b64 v52, v[88:89] offset:4096

.Lsm1_g5:
	s_bitcmp1_b32 s100, 5
	s_cbranch_scc0 .Lsm1_g6
	v_max_f32_e32 v52, v51, v51
	s_waitcnt lgkmcnt(0)
	v_max_f32_e32 v53, v50, v50
	v_max_f32_e32 v52, v53, v52
	v_max_f32_e32 v53, v47, v47
	v_max_f32_e32 v54, v46, v46
	v_max_f32_e32 v53, v54, v53
	v_max3_f32 v52, v48, v49, v52
	v_max3_f32 v53, v44, v45, v53
	v_max3_f32 v52, v52, s62, v53
	v_max_f32_e32 v53, v43, v43
	v_max_f32_e32 v54, v42, v42
	v_max_f32_e32 v53, v54, v53
	v_max_f32_e32 v54, v39, v39
	v_max_f32_e32 v55, v38, v38
	v_max_f32_e32 v54, v55, v54
	v_max3_f32 v53, v40, v41, v53
	v_max3_f32 v54, v36, v37, v54
	v_max3_f32 v52, v52, v53, v54
	ds_bpermute_b32 v53, v154, v52
	s_waitcnt lgkmcnt(0)
	v_max_f32_e32 v53, v53, v53
	v_max_f32_e32 v52, v52, v53
	ds_bpermute_b32 v53, v155, v52
	s_waitcnt lgkmcnt(0)
	v_max_f32_e32 v53, v53, v53
	v_max_f32_e32 v88, v52, v53
	v_sub_f32_e32 v48, v48, v88
	v_mul_f32_e32 v48, 0x3fb8aa3b, v48
	v_sub_f32_e32 v49, v49, v88
	v_exp_f32_e32 v48, v48
	v_mul_f32_e32 v49, 0x3fb8aa3b, v49
	v_sub_f32_e32 v50, v50, v88
	v_exp_f32_e32 v49, v49
	v_mul_f32_e32 v50, 0x3fb8aa3b, v50
	v_sub_f32_e32 v51, v51, v88
	v_exp_f32_e32 v50, v50
	v_mul_f32_e32 v51, 0x3fb8aa3b, v51
	v_exp_f32_e32 v51, v51
	v_add_f32_e32 v52, 0, v48
	v_add_f32_e32 v52, v49, v52
	v_sub_f32_e32 v44, v44, v88
	v_add_f32_e32 v52, v50, v52
	v_mul_f32_e32 v44, 0x3fb8aa3b, v44
	v_add_f32_e32 v54, v51, v52
	v_exp_f32_e32 v52, v44
	v_sub_f32_e32 v44, v45, v88
	v_mul_f32_e32 v44, 0x3fb8aa3b, v44
	v_exp_f32_e32 v53, v44
	v_sub_f32_e32 v44, v46, v88
	v_mul_f32_e32 v44, 0x3fb8aa3b, v44
	v_exp_f32_e32 v56, v44
	v_sub_f32_e32 v44, v47, v88
	v_mul_f32_e32 v44, 0x3fb8aa3b, v44
	v_exp_f32_e32 v57, v44
	v_add_f32_e32 v44, v52, v54
	v_add_f32_e32 v44, v53, v44
	v_sub_f32_e32 v40, v40, v88
	v_add_f32_e32 v44, v56, v44
	v_mul_f32_e32 v40, 0x3fb8aa3b, v40
	v_add_f32_e32 v54, v57, v44
	v_exp_f32_e32 v44, v40
	v_sub_f32_e32 v40, v41, v88
	v_mul_f32_e32 v40, 0x3fb8aa3b, v40
	v_exp_f32_e32 v45, v40
	v_sub_f32_e32 v40, v42, v88
	v_mul_f32_e32 v40, 0x3fb8aa3b, v40
	v_exp_f32_e32 v46, v40
	v_sub_f32_e32 v40, v43, v88
	v_sub_f32_e32 v36, v36, v88
	v_mul_f32_e32 v40, 0x3fb8aa3b, v40
	v_mul_f32_e32 v36, 0x3fb8aa3b, v36
	v_exp_f32_e32 v47, v40
	v_add_f32_e32 v40, v44, v54
	v_exp_f32_e32 v54, v36
	v_sub_f32_e32 v36, v37, v88
	v_mul_f32_e32 v36, 0x3fb8aa3b, v36
	v_exp_f32_e32 v55, v36
	v_sub_f32_e32 v36, v38, v88
	v_mul_f32_e32 v36, 0x3fb8aa3b, v36
	v_add_f32_e32 v40, v45, v40
	v_exp_f32_e32 v58, v36
	v_sub_f32_e32 v36, v39, v88
	v_add_f32_e32 v40, v46, v40
	v_mul_f32_e32 v36, 0x3fb8aa3b, v36
	v_add_f32_e32 v40, v47, v40
	v_exp_f32_e32 v59, v36
	v_add_f32_e32 v36, v54, v40
	v_add_f32_e32 v36, v55, v36
	v_add_f32_e32 v36, v58, v36
	v_add_f32_e32 v36, v59, v36
	ds_bpermute_b32 v37, v154, v36
	s_waitcnt lgkmcnt(0)
	v_add_f32_e32 v36, v36, v37
	ds_bpermute_b32 v37, v155, v36
	s_and_saveexec_b64 s[8:9], vcc
	s_cbranch_execz .LBB0_563
	s_lshl_b32 s44, s28, 11
	s_add_i32 s44, s29, s44
	s_waitcnt lgkmcnt(0)
	v_add_f32_e32 v89, v36, v37
	v_lshl_add_u32 v36, v153, 5, s44
	ds_write_b64 v36, v[88:89] offset:4608

.Lsm1_g6:
	s_bitcmp1_b32 s100, 6
	s_cbranch_scc0 .Lsm1_g7
	v_max_f32_e32 v36, v35, v35
	s_waitcnt lgkmcnt(0)
	v_max_f32_e32 v37, v34, v34
	v_max_f32_e32 v36, v37, v36
	v_max_f32_e32 v37, v31, v31
	v_max_f32_e32 v38, v30, v30
	v_max_f32_e32 v37, v38, v37
	v_max3_f32 v36, v32, v33, v36
	v_max3_f32 v37, v28, v29, v37
	v_max3_f32 v36, v36, s62, v37
	v_max_f32_e32 v37, v27, v27
	v_max_f32_e32 v38, v26, v26
	v_max_f32_e32 v37, v38, v37
	v_max_f32_e32 v38, v23, v23
	v_max_f32_e32 v39, v22, v22
	v_max_f32_e32 v38, v39, v38
	v_max3_f32 v37, v24, v25, v37
	v_max3_f32 v38, v20, v21, v38
	v_max3_f32 v36, v36, v37, v38
	ds_bpermute_b32 v37, v154, v36
	s_waitcnt lgkmcnt(0)
	v_max_f32_e32 v37, v37, v37
	v_max_f32_e32 v36, v36, v37
	ds_bpermute_b32 v37, v155, v36
	s_waitcnt lgkmcnt(0)
	v_max_f32_e32 v37, v37, v37
	v_max_f32_e32 v88, v36, v37
	v_sub_f32_e32 v32, v32, v88
	v_mul_f32_e32 v32, 0x3fb8aa3b, v32
	v_sub_f32_e32 v33, v33, v88
	v_exp_f32_e32 v32, v32
	v_mul_f32_e32 v33, 0x3fb8aa3b, v33
	v_sub_f32_e32 v34, v34, v88
	v_exp_f32_e32 v33, v33
	v_mul_f32_e32 v34, 0x3fb8aa3b, v34
	v_sub_f32_e32 v35, v35, v88
	v_exp_f32_e32 v34, v34
	v_mul_f32_e32 v35, 0x3fb8aa3b, v35
	v_exp_f32_e32 v35, v35
	v_add_f32_e32 v36, 0, v32
	v_add_f32_e32 v36, v33, v36
	v_sub_f32_e32 v28, v28, v88
	v_add_f32_e32 v36, v34, v36
	v_mul_f32_e32 v28, 0x3fb8aa3b, v28
	v_add_f32_e32 v38, v35, v36
	v_exp_f32_e32 v36, v28
	v_sub_f32_e32 v28, v29, v88
	v_mul_f32_e32 v28, 0x3fb8aa3b, v28
	v_exp_f32_e32 v37, v28
	v_sub_f32_e32 v28, v30, v88
	v_mul_f32_e32 v28, 0x3fb8aa3b, v28
	v_exp_f32_e32 v40, v28
	v_sub_f32_e32 v28, v31, v88
	v_mul_f32_e32 v28, 0x3fb8aa3b, v28
	v_exp_f32_e32 v41, v28
	v_add_f32_e32 v28, v36, v38
	v_add_f32_e32 v28, v37, v28
	v_sub_f32_e32 v24, v24, v88
	v_add_f32_e32 v28, v40, v28
	v_mul_f32_e32 v24, 0x3fb8aa3b, v24
	v_add_f32_e32 v38, v41, v28
	v_exp_f32_e32 v28, v24
	v_sub_f32_e32 v24, v25, v88
	v_mul_f32_e32 v24, 0x3fb8aa3b, v24
	v_exp_f32_e32 v29, v24
	v_sub_f32_e32 v24, v26, v88
	v_mul_f32_e32 v24, 0x3fb8aa3b, v24
	v_exp_f32_e32 v30, v24
	v_sub_f32_e32 v24, v27, v88
	v_sub_f32_e32 v20, v20, v88
	v_mul_f32_e32 v24, 0x3fb8aa3b, v24
	v_mul_f32_e32 v20, 0x3fb8aa3b, v20
	v_exp_f32_e32 v31, v24
	v_add_f32_e32 v24, v28, v38
	v_exp_f32_e32 v38, v20
	v_sub_f32_e32 v20, v21, v88
	v_mul_f32_e32 v20, 0x3fb8aa3b, v20
	v_exp_f32_e32 v39, v20
	v_sub_f32_e32 v20, v22, v88
	v_mul_f32_e32 v20, 0x3fb8aa3b, v20
	v_add_f32_e32 v24, v29, v24
	v_exp_f32_e32 v42, v20
	v_sub_f32_e32 v20, v23, v88
	v_add_f32_e32 v24, v30, v24
	v_mul_f32_e32 v20, 0x3fb8aa3b, v20
	v_add_f32_e32 v24, v31, v24
	v_exp_f32_e32 v43, v20
	v_add_f32_e32 v20, v38, v24
	v_add_f32_e32 v20, v39, v20
	v_add_f32_e32 v20, v42, v20
	v_add_f32_e32 v20, v43, v20
	ds_bpermute_b32 v21, v154, v20
	s_waitcnt lgkmcnt(0)
	v_add_f32_e32 v20, v20, v21
	ds_bpermute_b32 v21, v155, v20
	s_and_saveexec_b64 s[8:9], vcc
	s_cbranch_execz .LBB0_565
	s_lshl_b32 s44, s28, 11
	s_add_i32 s44, s29, s44
	s_waitcnt lgkmcnt(0)
	v_add_f32_e32 v89, v20, v21
	v_lshl_add_u32 v20, v153, 5, s44
	ds_write_b64 v20, v[88:89] offset:5120

.Lsm1_g7:
	s_bitcmp1_b32 s100, 7
	s_cbranch_scc0 .Lsm1_g8
	v_max_f32_e32 v20, v19, v19
	s_waitcnt lgkmcnt(0)
	v_max_f32_e32 v21, v18, v18
	v_max_f32_e32 v20, v21, v20
	v_max_f32_e32 v21, v15, v15
	v_max_f32_e32 v22, v14, v14
	v_max_f32_e32 v21, v22, v21
	v_max3_f32 v20, v16, v17, v20
	v_max3_f32 v21, v12, v13, v21
	v_max3_f32 v20, v20, s62, v21
	v_max_f32_e32 v21, v11, v11
	v_max_f32_e32 v22, v10, v10
	v_max_f32_e32 v21, v22, v21
	v_max_f32_e32 v22, v7, v7
	v_max_f32_e32 v23, v6, v6
	v_max_f32_e32 v22, v23, v22
	v_max3_f32 v21, v8, v9, v21
	v_max3_f32 v22, v4, v5, v22
	v_max3_f32 v20, v20, v21, v22
	ds_bpermute_b32 v21, v154, v20
	s_waitcnt lgkmcnt(0)
	v_max_f32_e32 v21, v21, v21
	v_max_f32_e32 v20, v20, v21
	ds_bpermute_b32 v21, v155, v20
	s_waitcnt lgkmcnt(0)
	v_max_f32_e32 v21, v21, v21
	v_max_f32_e32 v88, v20, v21
	v_sub_f32_e32 v16, v16, v88
	v_mul_f32_e32 v16, 0x3fb8aa3b, v16
	v_sub_f32_e32 v17, v17, v88
	v_exp_f32_e32 v16, v16
	v_mul_f32_e32 v17, 0x3fb8aa3b, v17
	v_sub_f32_e32 v18, v18, v88
	v_exp_f32_e32 v17, v17
	v_mul_f32_e32 v18, 0x3fb8aa3b, v18
	v_sub_f32_e32 v19, v19, v88
	v_exp_f32_e32 v18, v18
	v_mul_f32_e32 v19, 0x3fb8aa3b, v19
	v_exp_f32_e32 v19, v19
	v_add_f32_e32 v20, 0, v16
	v_add_f32_e32 v20, v17, v20
	v_sub_f32_e32 v12, v12, v88
	v_add_f32_e32 v20, v18, v20
	v_mul_f32_e32 v12, 0x3fb8aa3b, v12
	v_add_f32_e32 v22, v19, v20
	v_exp_f32_e32 v20, v12
	v_sub_f32_e32 v12, v13, v88
	v_mul_f32_e32 v12, 0x3fb8aa3b, v12
	v_exp_f32_e32 v21, v12
	v_sub_f32_e32 v12, v14, v88
	v_mul_f32_e32 v12, 0x3fb8aa3b, v12
	v_exp_f32_e32 v24, v12
	v_sub_f32_e32 v12, v15, v88
	v_mul_f32_e32 v12, 0x3fb8aa3b, v12
	v_exp_f32_e32 v25, v12
	v_add_f32_e32 v12, v20, v22
	v_add_f32_e32 v12, v21, v12
	v_sub_f32_e32 v8, v8, v88
	v_add_f32_e32 v12, v24, v12
	v_mul_f32_e32 v8, 0x3fb8aa3b, v8
	v_add_f32_e32 v22, v25, v12
	v_exp_f32_e32 v12, v8
	v_sub_f32_e32 v8, v9, v88
	v_mul_f32_e32 v8, 0x3fb8aa3b, v8
	v_exp_f32_e32 v13, v8
	v_sub_f32_e32 v8, v10, v88
	v_mul_f32_e32 v8, 0x3fb8aa3b, v8
	v_exp_f32_e32 v14, v8
	v_sub_f32_e32 v8, v11, v88
	v_sub_f32_e32 v4, v4, v88
	v_mul_f32_e32 v8, 0x3fb8aa3b, v8
	v_mul_f32_e32 v4, 0x3fb8aa3b, v4
	v_exp_f32_e32 v15, v8
	v_add_f32_e32 v8, v12, v22
	v_exp_f32_e32 v22, v4
	v_sub_f32_e32 v4, v5, v88
	v_mul_f32_e32 v4, 0x3fb8aa3b, v4
	v_exp_f32_e32 v23, v4
	v_sub_f32_e32 v4, v6, v88
	v_mul_f32_e32 v4, 0x3fb8aa3b, v4
	v_add_f32_e32 v8, v13, v8
	v_exp_f32_e32 v26, v4
	v_sub_f32_e32 v4, v7, v88
	v_add_f32_e32 v8, v14, v8
	v_mul_f32_e32 v4, 0x3fb8aa3b, v4
	v_add_f32_e32 v8, v15, v8
	v_exp_f32_e32 v27, v4
	v_add_f32_e32 v4, v22, v8
	v_add_f32_e32 v4, v23, v4
	v_add_f32_e32 v4, v26, v4
	v_add_f32_e32 v4, v27, v4
	ds_bpermute_b32 v5, v154, v4
	s_waitcnt lgkmcnt(0)
	v_add_f32_e32 v4, v4, v5
	ds_bpermute_b32 v5, v155, v4
	s_and_saveexec_b64 s[8:9], vcc
	s_cbranch_execz .LBB0_567
	s_lshl_b32 s44, s28, 11
	s_add_i32 s29, s29, s44
	s_waitcnt lgkmcnt(0)
	v_add_f32_e32 v89, v4, v5
	v_lshl_add_u32 v4, v153, 5, s29
	ds_write_b64 v4, v[88:89] offset:5632

.Lsm1_g8:
	v_lshl_add_u32 v146, s28, 6, v153
	v_mbcnt_lo_u32_b32 v243, -1, 0
	v_mbcnt_hi_u32_b32 v243, -1, v243
	v_and_b32_e32 v244, 3, v243
	v_lshrrev_b32_e32 v245, 2, v243
	v_lshlrev_b32_e32 v242, 6, v244
	v_lshl_or_b32 v242, v245, 2, v242
	v_lshl_add_u32 v245, s28, 6, v245
	v_lshl_add_u32 v4, v146, 5, 0
	s_waitcnt lgkmcnt(0)
	s_barrier
	s_cmp_lg_u32 s100, 0
	s_cbranch_scc1 .Lsm2_go
	s_and_b64 vcc, exec, s[6:7]
	s_mov_b64 s[6:7], -1
	s_branch .Lsm2_join
.Lsm2_go:
	v_add_u32_e32 v4, 0x20000, v4
	ds_read_b128 v[8:11], v4
	s_waitcnt lgkmcnt(0)
	ds_read_b128 v[4:7], v4 offset:16
	s_cmp_eq_u32 s24, 2
	s_cselect_b64 s[8:9], -1, 0
	s_cmp_lt_i32 s24, 1
	s_cbranch_scc1 .LBB0_571
	s_cmp_eq_u32 s24, 1
	s_mov_b64 s[28:29], -1
	s_cbranch_scc0 .LBB0_570
	s_mov_b64 s[28:29], 0

.Lsm2_join:
	s_cbranch_vccnz .LBB0_534
	s_andn2_b64 vcc, exec, s[82:83]
	s_cbranch_vccnz .LBB0_533
	s_barrier
	s_branch .LBB0_533

	.amdhsa_kernel _Z9trunk_fwd4Args
		.amdhsa_group_segment_fixed_size 0
		.amdhsa_private_segment_fixed_size 0
		.amdhsa_kernarg_size 536
		.amdhsa_user_sgpr_count 2
		.amdhsa_user_sgpr_dispatch_ptr 0
		.amdhsa_user_sgpr_queue_ptr 0
		.amdhsa_user_sgpr_kernarg_segment_ptr 1
		.amdhsa_user_sgpr_dispatch_id 0
		.amdhsa_user_sgpr_kernarg_preload_length 0
		.amdhsa_user_sgpr_kernarg_preload_offset 0
		.amdhsa_user_sgpr_private_segment_size 0
		.amdhsa_uses_dynamic_stack 0
		.amdhsa_enable_private_segment 0
		.amdhsa_system_sgpr_workgroup_id_x 1
		.amdhsa_system_sgpr_workgroup_id_y 0
		.amdhsa_system_sgpr_workgroup_id_z 0
		.amdhsa_system_sgpr_workgroup_info 0
		.amdhsa_system_vgpr_workitem_id 2
		.amdhsa_next_free_vgpr 256
		.amdhsa_next_free_sgpr 102
		.amdhsa_accum_offset 256
		.amdhsa_reserve_vcc 1
		.amdhsa_float_round_mode_32 0
		.amdhsa_float_round_mode_16_64 0
		.amdhsa_float_denorm_mode_32 3
		.amdhsa_float_denorm_mode_16_64 3
		.amdhsa_dx10_clamp 1
		.amdhsa_ieee_mode 1
		.amdhsa_fp16_overflow 0
		.amdhsa_tg_split 0
		.amdhsa_exception_fp_ieee_invalid_op 0
		.amdhsa_exception_fp_denorm_src 0
		.amdhsa_exception_fp_ieee_div_zero 0
		.amdhsa_exception_fp_ieee_overflow 0
		.amdhsa_exception_fp_ieee_underflow 0
		.amdhsa_exception_fp_ieee_inexact 0
		.amdhsa_exception_int_div_zero 0
	.end_amdhsa_kernel

amdhsa.kernels:
  - .agpr_count:     0
    .args:
      - .offset:         0
        .size:           280
        .value_kind:     by_value
      - .offset:         280
        .size:           4
        .value_kind:     hidden_block_count_x
      - .offset:         284
        .size:           4
        .value_kind:     hidden_block_count_y
      - .offset:         288
        .size:           4
        .value_kind:     hidden_block_count_z
      - .offset:         292
        .size:           2
        .value_kind:     hidden_group_size_x
      - .offset:         294
        .size:           2
        .value_kind:     hidden_group_size_y
      - .offset:         296
        .size:           2
        .value_kind:     hidden_group_size_z
      - .offset:         298
        .size:           2
        .value_kind:     hidden_remainder_x
      - .offset:         300
        .size:           2
        .value_kind:     hidden_remainder_y
      - .offset:         302
        .size:           2
        .value_kind:     hidden_remainder_z
      - .offset:         320
        .size:           8
        .value_kind:     hidden_global_offset_x
      - .offset:         328
        .size:           8
        .value_kind:     hidden_global_offset_y
      - .offset:         336
        .size:           8
        .value_kind:     hidden_global_offset_z
      - .offset:         344
        .size:           2
        .value_kind:     hidden_grid_dims
      - .offset:         368
        .size:           8
        .value_kind:     hidden_multigrid_sync_arg
      - .offset:         400
        .size:           4
        .value_kind:     hidden_dynamic_lds_size
    .group_segment_fixed_size: 0
    .kernarg_segment_align: 8
    .kernarg_segment_size: 536
    .language:       OpenCL C
    .language_version:
      - 2
      - 0
    .max_flat_workgroup_size: 512
    .name:           _Z9trunk_fwd4Args
    .private_segment_fixed_size: 0
    .sgpr_count:     108
    .sgpr_spill_count: 130
    .symbol:         _Z9trunk_fwd4Args.kd
    .uniform_work_group_size: 1
    .uses_dynamic_stack: false
    .vgpr_count:     256
    .vgpr_spill_count: 0
    .wavefront_size: 64
